# HGRN pass-1 item rewritten by hand: chunk-end state computed as W^T x I on v_mfma_f32_16x16x4_f32 (f32 in, f32 accumulate) with suffix products of the forget gates, instead of the 128-step serial recu
# speedup vs baseline: 1.0061x; 1.0061x over previous
.LBB0_849:
	s_or_b64 exec, exec, s[0:1]
	s_waitcnt lgkmcnt(0)
	s_barrier
	ds_read_b32 v0, v173
	s_mov_b64 s[0:1], -1
	s_waitcnt lgkmcnt(0)
	v_cmp_le_i32_e32 vcc, s65, v0
	v_readfirstlane_b32 s76, v0
	s_cbranch_vccnz .LBB0_844
	s_cmp_ge_i32 s76, s64
	s_cbranch_scc0 .LBB0_921
	s_sub_i32 s77, s76, s64
	s_cmpk_gt_i32 s77, 0x1ff
	s_cbranch_scc0 .LBB0_906
	s_cmpk_gt_u32 s77, 0x7ff
	s_cbranch_scc0 .LBB0_895
	s_add_i32 s28, s77, 0xfffff800
	s_and_b32 s0, s28, 31
	s_bfe_u32 s1, s28, 0x20005
	s_lshr_b32 s26, s28, 7
	s_lshl_b32 s26, s26, 12
	s_lshl_b32 s0, s0, 7
	s_add_i32 s26, s26, s0
	s_mul_hi_u32 s27, s26, 0x4600
	s_mul_i32 s0, s26, 0x4600
	s_lshl_b32 s29, s1, 7
	s_add_u32 s44, s92, s0
	s_addc_u32 s45, s93, s27
	s_add_u32 s44, s44, 0x23604900
	s_addc_u32 s45, s45, 0
	s_add_u32 s44, s44, s29
	s_addc_u32 s45, s45, 0
	s_add_u32 s44, s44, 0x2000
	s_addc_u32 s45, s45, 0
	v_lshrrev_b32_e32 v0, 3, v166
	v_and_b32_e32 v1, 7, v166
	v_mul_u32_u24_e32 v2, 0x4600, v0
	v_lshl_add_u32 v2, v1, 4, v2
	v_add_u32_e32 v3, 0x118000, v2
	global_load_dwordx4 v[4:7], v2, s[44:45]
	global_load_dwordx4 v[8:11], v2, s[44:45] offset:512
	global_load_dwordx4 v[12:15], v3, s[44:45]
	global_load_dwordx4 v[16:19], v3, s[44:45] offset:512
	v_readlane_b32 s30, v241, 20
	v_readlane_b32 s31, v241, 21
	v_mov_b32_e32 v20, 0
	v_mov_b32_e32 v21, 0
	v_mov_b32_e32 v22, 0
	v_mov_b32_e32 v23, 0
	v_mov_b32_e32 v24, 0
	v_mov_b32_e32 v25, 0
	v_mov_b32_e32 v26, 0
	v_mov_b32_e32 v27, 0
	s_nop 0
	s_and_b64 vcc, exec, s[30:31]
	s_cbranch_vccz .Lh1_nolb
	v_readlane_b32 s58, v245, 14
	v_readlane_b32 s59, v245, 15
	s_lshl_b32 s29, s1, 8
	v_lshl_add_u32 v36, v1, 5, s29
	s_nop 3
	global_load_dwordx4 v[40:43], v36, s[58:59]
	global_load_dwordx4 v[44:47], v36, s[58:59] offset:16
	global_load_dwordx4 v[48:51], v36, s[58:59] offset:1024
	global_load_dwordx4 v[52:55], v36, s[58:59] offset:1040
	s_waitcnt vmcnt(0)
	v_sub_f32_e32 v56, v40, v48
	v_mul_f32_e32 v56, 0x3fb8aa3b, v56
	v_exp_f32_e32 v56, v56
	s_nop 0
	v_add_f32_e32 v56, 1.0, v56
	v_div_scale_f32 v57, s[36:37], v56, v56, 1.0
	v_rcp_f32_e32 v58, v57
	v_div_scale_f32 v59, vcc, 1.0, v56, 1.0
	v_fma_f32 v60, -v57, v58, 1.0
	v_fmac_f32_e32 v58, v60, v58
	v_mul_f32_e32 v60, v59, v58
	v_fma_f32 v61, -v57, v60, v59
	v_fmac_f32_e32 v60, v61, v58
	v_fma_f32 v57, -v57, v60, v59
	v_div_fmas_f32 v57, v57, v58, v60
	v_div_fixup_f32 v20, v57, v56, 1.0
	v_sub_f32_e32 v56, v41, v49
	v_mul_f32_e32 v56, 0x3fb8aa3b, v56
	v_exp_f32_e32 v56, v56
	s_nop 0
	v_add_f32_e32 v56, 1.0, v56
	v_div_scale_f32 v57, s[36:37], v56, v56, 1.0
	v_rcp_f32_e32 v58, v57
	v_div_scale_f32 v59, vcc, 1.0, v56, 1.0
	v_fma_f32 v60, -v57, v58, 1.0
	v_fmac_f32_e32 v58, v60, v58
	v_mul_f32_e32 v60, v59, v58
	v_fma_f32 v61, -v57, v60, v59
	v_fmac_f32_e32 v60, v61, v58
	v_fma_f32 v57, -v57, v60, v59
	v_div_fmas_f32 v57, v57, v58, v60
	v_div_fixup_f32 v21, v57, v56, 1.0
	v_sub_f32_e32 v56, v42, v50
	v_mul_f32_e32 v56, 0x3fb8aa3b, v56
	v_exp_f32_e32 v56, v56
	s_nop 0
	v_add_f32_e32 v56, 1.0, v56
	v_div_scale_f32 v57, s[36:37], v56, v56, 1.0
	v_rcp_f32_e32 v58, v57
	v_div_scale_f32 v59, vcc, 1.0, v56, 1.0
	v_fma_f32 v60, -v57, v58, 1.0
	v_fmac_f32_e32 v58, v60, v58
	v_mul_f32_e32 v60, v59, v58
	v_fma_f32 v61, -v57, v60, v59
	v_fmac_f32_e32 v60, v61, v58
	v_fma_f32 v57, -v57, v60, v59
	v_div_fmas_f32 v57, v57, v58, v60
	v_div_fixup_f32 v22, v57, v56, 1.0
	v_sub_f32_e32 v56, v43, v51
	v_mul_f32_e32 v56, 0x3fb8aa3b, v56
	v_exp_f32_e32 v56, v56
	s_nop 0
	v_add_f32_e32 v56, 1.0, v56
	v_div_scale_f32 v57, s[36:37], v56, v56, 1.0
	v_rcp_f32_e32 v58, v57
	v_div_scale_f32 v59, vcc, 1.0, v56, 1.0
	v_fma_f32 v60, -v57, v58, 1.0
	v_fmac_f32_e32 v58, v60, v58
	v_mul_f32_e32 v60, v59, v58
	v_fma_f32 v61, -v57, v60, v59
	v_fmac_f32_e32 v60, v61, v58
	v_fma_f32 v57, -v57, v60, v59
	v_div_fmas_f32 v57, v57, v58, v60
	v_div_fixup_f32 v23, v57, v56, 1.0
	v_sub_f32_e32 v56, v44, v52
	v_mul_f32_e32 v56, 0x3fb8aa3b, v56
	v_exp_f32_e32 v56, v56
	s_nop 0
	v_add_f32_e32 v56, 1.0, v56
	v_div_scale_f32 v57, s[36:37], v56, v56, 1.0
	v_rcp_f32_e32 v58, v57
	v_div_scale_f32 v59, vcc, 1.0, v56, 1.0
	v_fma_f32 v60, -v57, v58, 1.0
	v_fmac_f32_e32 v58, v60, v58
	v_mul_f32_e32 v60, v59, v58
	v_fma_f32 v61, -v57, v60, v59
	v_fmac_f32_e32 v60, v61, v58
	v_fma_f32 v57, -v57, v60, v59
	v_div_fmas_f32 v57, v57, v58, v60
	v_div_fixup_f32 v24, v57, v56, 1.0
	v_sub_f32_e32 v56, v45, v53
	v_mul_f32_e32 v56, 0x3fb8aa3b, v56
	v_exp_f32_e32 v56, v56
	s_nop 0
	v_add_f32_e32 v56, 1.0, v56
	v_div_scale_f32 v57, s[36:37], v56, v56, 1.0
	v_rcp_f32_e32 v58, v57
	v_div_scale_f32 v59, vcc, 1.0, v56, 1.0
	v_fma_f32 v60, -v57, v58, 1.0
	v_fmac_f32_e32 v58, v60, v58
	v_mul_f32_e32 v60, v59, v58
	v_fma_f32 v61, -v57, v60, v59
	v_fmac_f32_e32 v60, v61, v58
	v_fma_f32 v57, -v57, v60, v59
	v_div_fmas_f32 v57, v57, v58, v60
	v_div_fixup_f32 v25, v57, v56, 1.0
	v_sub_f32_e32 v56, v46, v54
	v_mul_f32_e32 v56, 0x3fb8aa3b, v56
	v_exp_f32_e32 v56, v56
	s_nop 0
	v_add_f32_e32 v56, 1.0, v56
	v_div_scale_f32 v57, s[36:37], v56, v56, 1.0
	v_rcp_f32_e32 v58, v57
	v_div_scale_f32 v59, vcc, 1.0, v56, 1.0
	v_fma_f32 v60, -v57, v58, 1.0
	v_fmac_f32_e32 v58, v60, v58
	v_mul_f32_e32 v60, v59, v58
	v_fma_f32 v61, -v57, v60, v59
	v_fmac_f32_e32 v60, v61, v58
	v_fma_f32 v57, -v57, v60, v59
	v_div_fmas_f32 v57, v57, v58, v60
	v_div_fixup_f32 v26, v57, v56, 1.0
	v_sub_f32_e32 v56, v47, v55
	v_mul_f32_e32 v56, 0x3fb8aa3b, v56
	v_exp_f32_e32 v56, v56
	s_nop 0
	v_add_f32_e32 v56, 1.0, v56
	v_div_scale_f32 v57, s[36:37], v56, v56, 1.0
	v_rcp_f32_e32 v58, v57
	v_div_scale_f32 v59, vcc, 1.0, v56, 1.0
	v_fma_f32 v60, -v57, v58, 1.0
	v_fmac_f32_e32 v58, v60, v58
	v_mul_f32_e32 v60, v59, v58
	v_fma_f32 v61, -v57, v60, v59
	v_fmac_f32_e32 v60, v61, v58
	v_fma_f32 v57, -v57, v60, v59
	v_div_fmas_f32 v57, v57, v58, v60
	v_div_fixup_f32 v27, v57, v56, 1.0
.Lh1_nolb:
	v_sub_f32_e32 v28, 1.0, v20
	v_sub_f32_e32 v29, 1.0, v21
	v_sub_f32_e32 v30, 1.0, v22
	v_sub_f32_e32 v31, 1.0, v23
	v_sub_f32_e32 v32, 1.0, v24
	v_sub_f32_e32 v33, 1.0, v25
	v_sub_f32_e32 v34, 1.0, v26
	v_sub_f32_e32 v35, 1.0, v27
	v_mul_u32_u24_e32 v36, 0x1080, v1
	v_lshl_add_u32 v36, v0, 2, v36
	v_add_u32_e32 v37, 0x10800, v36
	s_waitcnt vmcnt(0)
	s_barrier
	v_lshlrev_b32_e32 v38, 16, v4
	v_lshlrev_b32_e32 v41, 16, v8
	v_mul_f32_e32 v39, 0xbfb8aa3b, v38
	v_mul_f32_e32 v40, 0x3fb8aa3b, v38
	v_exp_f32_e32 v39, v39
	v_exp_f32_e32 v40, v40
	v_add_f32_e32 v39, 1.0, v39
	v_add_f32_e32 v40, 1.0, v40
	v_rcp_f32_e32 v39, v39
	v_rcp_f32_e32 v40, v40
	v_fma_f32 v39, v28, v39, v20
	v_mul_f32_e32 v40, v28, v40
	ds_write_b32 v36, v39 offset:0
	ds_write_b32 v36, v40 offset:33792
	ds_write_b32 v37, v41 offset:0
	v_and_b32_e32 v38, 0xffff0000, v4
	v_and_b32_e32 v41, 0xffff0000, v8
	v_mul_f32_e32 v39, 0xbfb8aa3b, v38
	v_mul_f32_e32 v40, 0x3fb8aa3b, v38
	v_exp_f32_e32 v39, v39
	v_exp_f32_e32 v40, v40
	v_add_f32_e32 v39, 1.0, v39
	v_add_f32_e32 v40, 1.0, v40
	v_rcp_f32_e32 v39, v39
	v_rcp_f32_e32 v40, v40
	v_fma_f32 v39, v29, v39, v21
	v_mul_f32_e32 v40, v29, v40
	ds_write_b32 v36, v39 offset:528
	ds_write_b32 v36, v40 offset:34320
	ds_write_b32 v37, v41 offset:528
	v_lshlrev_b32_e32 v38, 16, v5
	v_lshlrev_b32_e32 v41, 16, v9
	v_mul_f32_e32 v39, 0xbfb8aa3b, v38
	v_mul_f32_e32 v40, 0x3fb8aa3b, v38
	v_exp_f32_e32 v39, v39
	v_exp_f32_e32 v40, v40
	v_add_f32_e32 v39, 1.0, v39
	v_add_f32_e32 v40, 1.0, v40
	v_rcp_f32_e32 v39, v39
	v_rcp_f32_e32 v40, v40
	v_fma_f32 v39, v30, v39, v22
	v_mul_f32_e32 v40, v30, v40
	ds_write_b32 v36, v39 offset:1056
	ds_write_b32 v36, v40 offset:34848
	ds_write_b32 v37, v41 offset:1056
	v_and_b32_e32 v38, 0xffff0000, v5
	v_and_b32_e32 v41, 0xffff0000, v9
	v_mul_f32_e32 v39, 0xbfb8aa3b, v38
	v_mul_f32_e32 v40, 0x3fb8aa3b, v38
	v_exp_f32_e32 v39, v39
	v_exp_f32_e32 v40, v40
	v_add_f32_e32 v39, 1.0, v39
	v_add_f32_e32 v40, 1.0, v40
	v_rcp_f32_e32 v39, v39
	v_rcp_f32_e32 v40, v40
	v_fma_f32 v39, v31, v39, v23
	v_mul_f32_e32 v40, v31, v40
	ds_write_b32 v36, v39 offset:1584
	ds_write_b32 v36, v40 offset:35376
	ds_write_b32 v37, v41 offset:1584
	v_lshlrev_b32_e32 v38, 16, v6
	v_lshlrev_b32_e32 v41, 16, v10
	v_mul_f32_e32 v39, 0xbfb8aa3b, v38
	v_mul_f32_e32 v40, 0x3fb8aa3b, v38
	v_exp_f32_e32 v39, v39
	v_exp_f32_e32 v40, v40
	v_add_f32_e32 v39, 1.0, v39
	v_add_f32_e32 v40, 1.0, v40
	v_rcp_f32_e32 v39, v39
	v_rcp_f32_e32 v40, v40
	v_fma_f32 v39, v32, v39, v24
	v_mul_f32_e32 v40, v32, v40
	ds_write_b32 v36, v39 offset:2112
	ds_write_b32 v36, v40 offset:35904
	ds_write_b32 v37, v41 offset:2112
	v_and_b32_e32 v38, 0xffff0000, v6
	v_and_b32_e32 v41, 0xffff0000, v10
	v_mul_f32_e32 v39, 0xbfb8aa3b, v38
	v_mul_f32_e32 v40, 0x3fb8aa3b, v38
	v_exp_f32_e32 v39, v39
	v_exp_f32_e32 v40, v40
	v_add_f32_e32 v39, 1.0, v39
	v_add_f32_e32 v40, 1.0, v40
	v_rcp_f32_e32 v39, v39
	v_rcp_f32_e32 v40, v40
	v_fma_f32 v39, v33, v39, v25
	v_mul_f32_e32 v40, v33, v40
	ds_write_b32 v36, v39 offset:2640
	ds_write_b32 v36, v40 offset:36432
	ds_write_b32 v37, v41 offset:2640
	v_lshlrev_b32_e32 v38, 16, v7
	v_lshlrev_b32_e32 v41, 16, v11
	v_mul_f32_e32 v39, 0xbfb8aa3b, v38
	v_mul_f32_e32 v40, 0x3fb8aa3b, v38
	v_exp_f32_e32 v39, v39
	v_exp_f32_e32 v40, v40
	v_add_f32_e32 v39, 1.0, v39
	v_add_f32_e32 v40, 1.0, v40
	v_rcp_f32_e32 v39, v39
	v_rcp_f32_e32 v40, v40
	v_fma_f32 v39, v34, v39, v26
	v_mul_f32_e32 v40, v34, v40
	ds_write_b32 v36, v39 offset:3168
	ds_write_b32 v36, v40 offset:36960
	ds_write_b32 v37, v41 offset:3168
	v_and_b32_e32 v38, 0xffff0000, v7
	v_and_b32_e32 v41, 0xffff0000, v11
	v_mul_f32_e32 v39, 0xbfb8aa3b, v38
	v_mul_f32_e32 v40, 0x3fb8aa3b, v38
	v_exp_f32_e32 v39, v39
	v_exp_f32_e32 v40, v40
	v_add_f32_e32 v39, 1.0, v39
	v_add_f32_e32 v40, 1.0, v40
	v_rcp_f32_e32 v39, v39
	v_rcp_f32_e32 v40, v40
	v_fma_f32 v39, v35, v39, v27
	v_mul_f32_e32 v40, v35, v40
	ds_write_b32 v36, v39 offset:3696
	ds_write_b32 v36, v40 offset:37488
	ds_write_b32 v37, v41 offset:3696
	v_lshlrev_b32_e32 v38, 16, v12
	v_lshlrev_b32_e32 v41, 16, v16
	v_mul_f32_e32 v39, 0xbfb8aa3b, v38
	v_mul_f32_e32 v40, 0x3fb8aa3b, v38
	v_exp_f32_e32 v39, v39
	v_exp_f32_e32 v40, v40
	v_add_f32_e32 v39, 1.0, v39
	v_add_f32_e32 v40, 1.0, v40
	v_rcp_f32_e32 v39, v39
	v_rcp_f32_e32 v40, v40
	v_fma_f32 v39, v28, v39, v20
	v_mul_f32_e32 v40, v28, v40
	ds_write_b32 v36, v39 offset:256
	ds_write_b32 v36, v40 offset:34048
	ds_write_b32 v37, v41 offset:256
	v_and_b32_e32 v38, 0xffff0000, v12
	v_and_b32_e32 v41, 0xffff0000, v16
	v_mul_f32_e32 v39, 0xbfb8aa3b, v38
	v_mul_f32_e32 v40, 0x3fb8aa3b, v38
	v_exp_f32_e32 v39, v39
	v_exp_f32_e32 v40, v40
	v_add_f32_e32 v39, 1.0, v39
	v_add_f32_e32 v40, 1.0, v40
	v_rcp_f32_e32 v39, v39
	v_rcp_f32_e32 v40, v40
	v_fma_f32 v39, v29, v39, v21
	v_mul_f32_e32 v40, v29, v40
	ds_write_b32 v36, v39 offset:784
	ds_write_b32 v36, v40 offset:34576
	ds_write_b32 v37, v41 offset:784
	v_lshlrev_b32_e32 v38, 16, v13
	v_lshlrev_b32_e32 v41, 16, v17
	v_mul_f32_e32 v39, 0xbfb8aa3b, v38
	v_mul_f32_e32 v40, 0x3fb8aa3b, v38
	v_exp_f32_e32 v39, v39
	v_exp_f32_e32 v40, v40
	v_add_f32_e32 v39, 1.0, v39
	v_add_f32_e32 v40, 1.0, v40
	v_rcp_f32_e32 v39, v39
	v_rcp_f32_e32 v40, v40
	v_fma_f32 v39, v30, v39, v22
	v_mul_f32_e32 v40, v30, v40
	ds_write_b32 v36, v39 offset:1312
	ds_write_b32 v36, v40 offset:35104
	ds_write_b32 v37, v41 offset:1312
	v_and_b32_e32 v38, 0xffff0000, v13
	v_and_b32_e32 v41, 0xffff0000, v17
	v_mul_f32_e32 v39, 0xbfb8aa3b, v38
	v_mul_f32_e32 v40, 0x3fb8aa3b, v38
	v_exp_f32_e32 v39, v39
	v_exp_f32_e32 v40, v40
	v_add_f32_e32 v39, 1.0, v39
	v_add_f32_e32 v40, 1.0, v40
	v_rcp_f32_e32 v39, v39
	v_rcp_f32_e32 v40, v40
	v_fma_f32 v39, v31, v39, v23
	v_mul_f32_e32 v40, v31, v40
	ds_write_b32 v36, v39 offset:1840
	ds_write_b32 v36, v40 offset:35632
	ds_write_b32 v37, v41 offset:1840
	v_lshlrev_b32_e32 v38, 16, v14
	v_lshlrev_b32_e32 v41, 16, v18
	v_mul_f32_e32 v39, 0xbfb8aa3b, v38
	v_mul_f32_e32 v40, 0x3fb8aa3b, v38
	v_exp_f32_e32 v39, v39
	v_exp_f32_e32 v40, v40
	v_add_f32_e32 v39, 1.0, v39
	v_add_f32_e32 v40, 1.0, v40
	v_rcp_f32_e32 v39, v39
	v_rcp_f32_e32 v40, v40
	v_fma_f32 v39, v32, v39, v24
	v_mul_f32_e32 v40, v32, v40
	ds_write_b32 v36, v39 offset:2368
	ds_write_b32 v36, v40 offset:36160
	ds_write_b32 v37, v41 offset:2368
	v_and_b32_e32 v38, 0xffff0000, v14
	v_and_b32_e32 v41, 0xffff0000, v18
	v_mul_f32_e32 v39, 0xbfb8aa3b, v38
	v_mul_f32_e32 v40, 0x3fb8aa3b, v38
	v_exp_f32_e32 v39, v39
	v_exp_f32_e32 v40, v40
	v_add_f32_e32 v39, 1.0, v39
	v_add_f32_e32 v40, 1.0, v40
	v_rcp_f32_e32 v39, v39
	v_rcp_f32_e32 v40, v40
	v_fma_f32 v39, v33, v39, v25
	v_mul_f32_e32 v40, v33, v40
	ds_write_b32 v36, v39 offset:2896
	ds_write_b32 v36, v40 offset:36688
	ds_write_b32 v37, v41 offset:2896
	v_lshlrev_b32_e32 v38, 16, v15
	v_lshlrev_b32_e32 v41, 16, v19
	v_mul_f32_e32 v39, 0xbfb8aa3b, v38
	v_mul_f32_e32 v40, 0x3fb8aa3b, v38
	v_exp_f32_e32 v39, v39
	v_exp_f32_e32 v40, v40
	v_add_f32_e32 v39, 1.0, v39
	v_add_f32_e32 v40, 1.0, v40
	v_rcp_f32_e32 v39, v39
	v_rcp_f32_e32 v40, v40
	v_fma_f32 v39, v34, v39, v26
	v_mul_f32_e32 v40, v34, v40
	ds_write_b32 v36, v39 offset:3424
	ds_write_b32 v36, v40 offset:37216
	ds_write_b32 v37, v41 offset:3424
	v_and_b32_e32 v38, 0xffff0000, v15
	v_and_b32_e32 v41, 0xffff0000, v19
	v_mul_f32_e32 v39, 0xbfb8aa3b, v38
	v_mul_f32_e32 v40, 0x3fb8aa3b, v38
	v_exp_f32_e32 v39, v39
	v_exp_f32_e32 v40, v40
	v_add_f32_e32 v39, 1.0, v39
	v_add_f32_e32 v40, 1.0, v40
	v_rcp_f32_e32 v39, v39
	v_rcp_f32_e32 v40, v40
	v_fma_f32 v39, v35, v39, v27
	v_mul_f32_e32 v40, v35, v40
	ds_write_b32 v36, v39 offset:3952
	ds_write_b32 v36, v40 offset:37744
	ds_write_b32 v37, v41 offset:3952
	s_waitcnt lgkmcnt(0)
	s_barrier
	v_readfirstlane_b32 s29, v166
	v_and_b32_e32 v0, 63, v166
	s_nop 1
	s_lshr_b32 s29, s29, 6
	v_mul_u32_u24_e32 v1, 0x210, v0
	s_lshl_b32 s0, s29, 6
	v_add_u32_e32 v1, s0, v1
	ds_read_b128 v[4:7], v1 offset:0
	ds_read_b128 v[8:11], v1 offset:16
	ds_read_b128 v[12:15], v1 offset:32
	ds_read_b128 v[16:19], v1 offset:48
	ds_read_b128 v[20:23], v1 offset:33792
	ds_read_b128 v[24:27], v1 offset:33808
	ds_read_b128 v[28:31], v1 offset:33824
	ds_read_b128 v[32:35], v1 offset:33840
	s_waitcnt lgkmcnt(0)
	v_mov_b32_e32 v36, v19
	v_mul_f32_e32 v34, v34, v36
	v_mul_f32_e32 v36, v36, v18
	v_mul_f32_e32 v33, v33, v36
	v_mul_f32_e32 v36, v36, v17
	v_mul_f32_e32 v32, v32, v36
	v_mul_f32_e32 v36, v36, v16
	v_mul_f32_e32 v31, v31, v36
	v_mul_f32_e32 v36, v36, v15
	v_mul_f32_e32 v30, v30, v36
	v_mul_f32_e32 v36, v36, v14
	v_mul_f32_e32 v29, v29, v36
	v_mul_f32_e32 v36, v36, v13
	v_mul_f32_e32 v28, v28, v36
	v_mul_f32_e32 v36, v36, v12
	v_mul_f32_e32 v27, v27, v36
	v_mul_f32_e32 v36, v36, v11
	v_mul_f32_e32 v26, v26, v36
	v_mul_f32_e32 v36, v36, v10
	v_mul_f32_e32 v25, v25, v36
	v_mul_f32_e32 v36, v36, v9
	v_mul_f32_e32 v24, v24, v36
	v_mul_f32_e32 v36, v36, v8
	v_mul_f32_e32 v23, v23, v36
	v_mul_f32_e32 v36, v36, v7
	v_mul_f32_e32 v22, v22, v36
	v_mul_f32_e32 v36, v36, v6
	v_mul_f32_e32 v21, v21, v36
	v_mul_f32_e32 v36, v36, v5
	v_mul_f32_e32 v20, v20, v36
	v_mul_f32_e32 v36, v36, v4
	v_lshlrev_b32_e32 v37, 2, v0
	v_add_u32_e32 v38, s0, v37
	v_add_u32_e32 v38, s0, v38
	v_add_u32_e32 v38, s0, v38
	v_add_u32_e32 v38, s0, v38
	v_add_u32_e32 v38, 0x18c00, v38
	v_add_u32_e32 v40, 0x18c00, v37
	ds_write_b32 v38, v36
	s_waitcnt lgkmcnt(0)
	s_barrier
	ds_read_b32 v41, v40 offset:256
	ds_read_b32 v42, v40 offset:512
	ds_read_b32 v43, v40 offset:768
	ds_read_b32 v44, v40 offset:1024
	ds_read_b32 v45, v40 offset:1280
	ds_read_b32 v46, v40 offset:1536
	ds_read_b32 v47, v40 offset:1792
	v_mov_b32_e32 v39, 1.0
	s_waitcnt lgkmcnt(0)
	s_cmp_lt_u32 s29, 1
	s_cbranch_scc0 .Lh1_q1
	v_mul_f32_e32 v39, v39, v41
.Lh1_q1:
	s_cmp_lt_u32 s29, 2
	s_cbranch_scc0 .Lh1_q2
	v_mul_f32_e32 v39, v39, v42
.Lh1_q2:
	s_cmp_lt_u32 s29, 3
	s_cbranch_scc0 .Lh1_q3
	v_mul_f32_e32 v39, v39, v43
.Lh1_q3:
	s_cmp_lt_u32 s29, 4
	s_cbranch_scc0 .Lh1_q4
	v_mul_f32_e32 v39, v39, v44
.Lh1_q4:
	s_cmp_lt_u32 s29, 5
	s_cbranch_scc0 .Lh1_q5
	v_mul_f32_e32 v39, v39, v45
.Lh1_q5:
	s_cmp_lt_u32 s29, 6
	s_cbranch_scc0 .Lh1_q6
	v_mul_f32_e32 v39, v39, v46
.Lh1_q6:
	s_cmp_lt_u32 s29, 7
	s_cbranch_scc0 .Lh1_q7
	v_mul_f32_e32 v39, v39, v47
.Lh1_q7:
	v_mul_f32_e32 v20, v20, v39
	v_mul_f32_e32 v21, v21, v39
	v_mul_f32_e32 v22, v22, v39
	v_mul_f32_e32 v23, v23, v39
	v_mul_f32_e32 v24, v24, v39
	v_mul_f32_e32 v25, v25, v39
	v_mul_f32_e32 v26, v26, v39
	v_mul_f32_e32 v27, v27, v39
	v_mul_f32_e32 v28, v28, v39
	v_mul_f32_e32 v29, v29, v39
	v_mul_f32_e32 v30, v30, v39
	v_mul_f32_e32 v31, v31, v39
	v_mul_f32_e32 v32, v32, v39
	v_mul_f32_e32 v33, v33, v39
	v_mul_f32_e32 v34, v34, v39
	v_mul_f32_e32 v35, v35, v39
	ds_write_b128 v1, v[20:23] offset:33792
	ds_write_b128 v1, v[24:27] offset:33808
	ds_write_b128 v1, v[28:31] offset:33824
	ds_write_b128 v1, v[32:35] offset:33840
	s_cmp_lg_u32 s29, 0
	s_cbranch_scc1 .Lh1_nofp
	s_lshl_b32 s0, s28, 8
	s_add_u32 s36, s92, 0x35604900
	s_addc_u32 s37, s93, 0
	s_add_u32 s36, s36, s0
	s_addc_u32 s37, s37, 0
	v_mul_f32_e32 v36, v36, v39
	global_store_dword v37, v36, s[36:37]
.Lh1_nofp:
	s_waitcnt lgkmcnt(0)
	s_barrier
	v_and_b32_e32 v0, 15, v166
	v_bfe_u32 v1, v166, 4, 2
	s_lshr_b32 s0, s29, 1
	s_and_b32 s1, s29, 1
	s_lshl_b32 s26, s0, 4
	v_add_u32_e32 v2, s26, v0
	v_mul_u32_u24_e32 v2, 0x210, v2
	v_lshl_add_u32 v2, v1, 4, v2
	v_add_u32_e32 v2, 0x8400, v2
	s_lshl_b32 s27, s1, 5
	v_add_u32_e32 v3, s27, v0
	v_mul_u32_u24_e32 v3, 0x210, v3
	v_lshl_add_u32 v3, v1, 4, v3
	v_add_u32_e32 v3, 0x10800, v3
	v_mov_b32_e32 v132, 0
	v_mov_b32_e32 v133, 0
	v_mov_b32_e32 v134, 0
	v_mov_b32_e32 v135, 0
	v_mov_b32_e32 v136, 0
	v_mov_b32_e32 v137, 0
	v_mov_b32_e32 v138, 0
	v_mov_b32_e32 v139, 0
	ds_read_b128 v[20:23], v2 offset:0
	ds_read_b128 v[68:71], v3 offset:0
	ds_read_b128 v[100:103], v3 offset:8448
	ds_read_b128 v[24:27], v2 offset:64
	ds_read_b128 v[72:75], v3 offset:64
	ds_read_b128 v[104:107], v3 offset:8512
	ds_read_b128 v[28:31], v2 offset:128
	ds_read_b128 v[76:79], v3 offset:128
	ds_read_b128 v[108:111], v3 offset:8576
	ds_read_b128 v[32:35], v2 offset:192
	ds_read_b128 v[80:83], v3 offset:192
	ds_read_b128 v[112:115], v3 offset:8640
	ds_read_b128 v[36:39], v2 offset:256
	ds_read_b128 v[84:87], v3 offset:256
	ds_read_b128 v[116:119], v3 offset:8704
	ds_read_b128 v[40:43], v2 offset:320
	ds_read_b128 v[88:91], v3 offset:320
	ds_read_b128 v[120:123], v3 offset:8768
	ds_read_b128 v[44:47], v2 offset:384
	ds_read_b128 v[92:95], v3 offset:384
	ds_read_b128 v[124:127], v3 offset:8832
	ds_read_b128 v[48:51], v2 offset:448
	ds_read_b128 v[96:99], v3 offset:448
	ds_read_b128 v[128:131], v3 offset:8896
	s_waitcnt lgkmcnt(15)
	v_mfma_f32_16x16x4_f32 v[132:135], v20, v68, v[132:135]
	v_mfma_f32_16x16x4_f32 v[136:139], v20, v100, v[136:139]
	v_mfma_f32_16x16x4_f32 v[132:135], v21, v69, v[132:135]
	v_mfma_f32_16x16x4_f32 v[136:139], v21, v101, v[136:139]
	v_mfma_f32_16x16x4_f32 v[132:135], v22, v70, v[132:135]
	v_mfma_f32_16x16x4_f32 v[136:139], v22, v102, v[136:139]
	v_mfma_f32_16x16x4_f32 v[132:135], v23, v71, v[132:135]
	v_mfma_f32_16x16x4_f32 v[136:139], v23, v103, v[136:139]
	s_waitcnt lgkmcnt(15)
	v_mfma_f32_16x16x4_f32 v[132:135], v24, v72, v[132:135]
	v_mfma_f32_16x16x4_f32 v[136:139], v24, v104, v[136:139]
	v_mfma_f32_16x16x4_f32 v[132:135], v25, v73, v[132:135]
	v_mfma_f32_16x16x4_f32 v[136:139], v25, v105, v[136:139]
	v_mfma_f32_16x16x4_f32 v[132:135], v26, v74, v[132:135]
	v_mfma_f32_16x16x4_f32 v[136:139], v26, v106, v[136:139]
	v_mfma_f32_16x16x4_f32 v[132:135], v27, v75, v[132:135]
	v_mfma_f32_16x16x4_f32 v[136:139], v27, v107, v[136:139]
	s_waitcnt lgkmcnt(15)
	v_mfma_f32_16x16x4_f32 v[132:135], v28, v76, v[132:135]
	v_mfma_f32_16x16x4_f32 v[136:139], v28, v108, v[136:139]
	v_mfma_f32_16x16x4_f32 v[132:135], v29, v77, v[132:135]
	v_mfma_f32_16x16x4_f32 v[136:139], v29, v109, v[136:139]
	v_mfma_f32_16x16x4_f32 v[132:135], v30, v78, v[132:135]
	v_mfma_f32_16x16x4_f32 v[136:139], v30, v110, v[136:139]
	v_mfma_f32_16x16x4_f32 v[132:135], v31, v79, v[132:135]
	v_mfma_f32_16x16x4_f32 v[136:139], v31, v111, v[136:139]
	s_waitcnt lgkmcnt(12)
	v_mfma_f32_16x16x4_f32 v[132:135], v32, v80, v[132:135]
	v_mfma_f32_16x16x4_f32 v[136:139], v32, v112, v[136:139]
	v_mfma_f32_16x16x4_f32 v[132:135], v33, v81, v[132:135]
	v_mfma_f32_16x16x4_f32 v[136:139], v33, v113, v[136:139]
	v_mfma_f32_16x16x4_f32 v[132:135], v34, v82, v[132:135]
	v_mfma_f32_16x16x4_f32 v[136:139], v34, v114, v[136:139]
	v_mfma_f32_16x16x4_f32 v[132:135], v35, v83, v[132:135]
	v_mfma_f32_16x16x4_f32 v[136:139], v35, v115, v[136:139]
	s_waitcnt lgkmcnt(9)
	v_mfma_f32_16x16x4_f32 v[132:135], v36, v84, v[132:135]
	v_mfma_f32_16x16x4_f32 v[136:139], v36, v116, v[136:139]
	v_mfma_f32_16x16x4_f32 v[132:135], v37, v85, v[132:135]
	v_mfma_f32_16x16x4_f32 v[136:139], v37, v117, v[136:139]
	v_mfma_f32_16x16x4_f32 v[132:135], v38, v86, v[132:135]
	v_mfma_f32_16x16x4_f32 v[136:139], v38, v118, v[136:139]
	v_mfma_f32_16x16x4_f32 v[132:135], v39, v87, v[132:135]
	v_mfma_f32_16x16x4_f32 v[136:139], v39, v119, v[136:139]
	s_waitcnt lgkmcnt(6)
	v_mfma_f32_16x16x4_f32 v[132:135], v40, v88, v[132:135]
	v_mfma_f32_16x16x4_f32 v[136:139], v40, v120, v[136:139]
	v_mfma_f32_16x16x4_f32 v[132:135], v41, v89, v[132:135]
	v_mfma_f32_16x16x4_f32 v[136:139], v41, v121, v[136:139]
	v_mfma_f32_16x16x4_f32 v[132:135], v42, v90, v[132:135]
	v_mfma_f32_16x16x4_f32 v[136:139], v42, v122, v[136:139]
	v_mfma_f32_16x16x4_f32 v[132:135], v43, v91, v[132:135]
	v_mfma_f32_16x16x4_f32 v[136:139], v43, v123, v[136:139]
	s_waitcnt lgkmcnt(3)
	v_mfma_f32_16x16x4_f32 v[132:135], v44, v92, v[132:135]
	v_mfma_f32_16x16x4_f32 v[136:139], v44, v124, v[136:139]
	v_mfma_f32_16x16x4_f32 v[132:135], v45, v93, v[132:135]
	v_mfma_f32_16x16x4_f32 v[136:139], v45, v125, v[136:139]
	v_mfma_f32_16x16x4_f32 v[132:135], v46, v94, v[132:135]
	v_mfma_f32_16x16x4_f32 v[136:139], v46, v126, v[136:139]
	v_mfma_f32_16x16x4_f32 v[132:135], v47, v95, v[132:135]
	v_mfma_f32_16x16x4_f32 v[136:139], v47, v127, v[136:139]
	s_waitcnt lgkmcnt(0)
	v_mfma_f32_16x16x4_f32 v[132:135], v48, v96, v[132:135]
	v_mfma_f32_16x16x4_f32 v[136:139], v48, v128, v[136:139]
	v_mfma_f32_16x16x4_f32 v[132:135], v49, v97, v[132:135]
	v_mfma_f32_16x16x4_f32 v[136:139], v49, v129, v[136:139]
	v_mfma_f32_16x16x4_f32 v[132:135], v50, v98, v[132:135]
	v_mfma_f32_16x16x4_f32 v[136:139], v50, v130, v[136:139]
	v_mfma_f32_16x16x4_f32 v[132:135], v51, v99, v[132:135]
	v_mfma_f32_16x16x4_f32 v[136:139], v51, v131, v[136:139]
	v_lshl_add_u32 v4, v1, 2, s26
	v_lshlrev_b32_e32 v4, 8, v4
	v_add_u32_e32 v5, s27, v0
	v_lshl_add_u32 v4, v5, 2, v4
	s_lshl_b32 s0, s28, 14
	s_add_u32 s44, s92, 0x34e04900
	s_addc_u32 s45, s93, 0
	s_add_u32 s44, s44, s0
	s_addc_u32 s45, s45, 0
	s_nop 7
	s_nop 3
	global_store_dword v4, v132, s[44:45]
	global_store_dword v4, v133, s[44:45] offset:256
	global_store_dword v4, v134, s[44:45] offset:512
	global_store_dword v4, v135, s[44:45] offset:768
	global_store_dword v4, v136, s[44:45] offset:64
	global_store_dword v4, v137, s[44:45] offset:320
	global_store_dword v4, v138, s[44:45] offset:576
	global_store_dword v4, v139, s[44:45] offset:832
	s_mov_b64 s[0:1], 0
	s_branch .LBB0_895
	s_add_i32 s28, s77, 0xfffff800
	v_mov_b32_e32 v48, v166
	s_lshl_b32 s0, s28, 1
	v_lshlrev_b32_e32 v0, 3, v48
	v_readlane_b32 s30, v241, 20
	s_and_b32 s26, s0, 0xc0
	v_and_b32_e32 v49, 56, v0
	v_readlane_b32 s31, v241, 21
	v_or_b32_e32 v1, s26, v49
	v_mov_b32_e32 v0, 0
	v_cndmask_b32_e64 v2, 0, 1, s[30:31]
	v_cmp_ne_u32_e64 s[0:1], 1, v2
	s_andn2_b64 vcc, exec, s[30:31]
	v_lshlrev_b32_e32 v50, 2, v1
	s_cbranch_vccnz .LBB0_855
	v_readlane_b32 s44, v245, 0
	v_readlane_b32 s58, v245, 14
	v_readlane_b32 s59, v245, 15
	s_nop 4
	global_load_dword v0, v50, s[58:59]
	global_load_dword v1, v50, s[58:59] offset:1024
	v_readlane_b32 s45, v245, 1
	v_readlane_b32 s46, v245, 2
	v_readlane_b32 s47, v245, 3
	v_readlane_b32 s48, v245, 4
	v_readlane_b32 s49, v245, 5
	v_readlane_b32 s50, v245, 6
	v_readlane_b32 s51, v245, 7
	v_readlane_b32 s52, v245, 8
	v_readlane_b32 s53, v245, 9
	v_readlane_b32 s54, v245, 10
	v_readlane_b32 s55, v245, 11
	v_readlane_b32 s56, v245, 12
	v_readlane_b32 s57, v245, 13
	s_waitcnt vmcnt(0)
	v_sub_f32_e32 v0, v0, v1
	v_mul_f32_e32 v0, 0x3fb8aa3b, v0
	v_exp_f32_e32 v0, v0
	s_nop 0
	v_add_f32_e32 v0, 1.0, v0
	v_div_scale_f32 v1, s[30:31], v0, v0, 1.0
	v_rcp_f32_e32 v2, v1
	v_div_scale_f32 v3, vcc, 1.0, v0, 1.0
	v_fma_f32 v4, -v1, v2, 1.0
	v_fmac_f32_e32 v2, v4, v2
	v_mul_f32_e32 v4, v3, v2
	v_fma_f32 v5, -v1, v4, v3
	v_fmac_f32_e32 v4, v5, v2
	v_fma_f32 v1, -v1, v4, v3
	v_div_fmas_f32 v1, v1, v2, v4
	v_div_fixup_f32 v0, v1, v0, 1.0
